# P6 K-loop: 16 loop-invariant LDS fragment address adds hoisted out of the loop into spare VGPRs
# speedup vs baseline: 1.0047x; 1.0047x over previous
.LBB0_1370:
	s_add_u32 s53, s56, 0x100
	s_addc_u32 s72, s57, 0
	s_ashr_i32 s51, s50, 31
	s_lshl_b64 s[26:27], s[50:51], 21
	s_add_u32 s54, s30, s26
	s_addc_u32 s55, s31, s27
	s_and_b64 s[26:27], s[6:7], exec
	s_cselect_b32 s51, s55, s19
	s_cselect_b32 s73, s54, s18
	s_ashr_i32 s49, s48, 31
	s_lshl_b64 s[26:27], s[48:49], 21
	v_readlane_b32 s58, v254, 9
	v_readlane_b32 s59, v254, 10
	s_add_u32 s26, s58, s26
	s_addc_u32 s27, s59, s27
	s_and_b64 s[58:59], s[6:7], exec
	s_cselect_b32 s49, s27, s57
	s_cselect_b32 s76, s26, s56
	v_lshl_add_u64 v[140:141], s[18:19], 0, v[134:135]
	s_mov_b32 s77, -2
	s_mov_b64 s[56:57], 0
	v_add_u32_e32 v222, s64, v143
	v_add_u32_e32 v223, s64, v144
	v_add_u32_e32 v224, s65, v143
	v_add_u32_e32 v225, s65, v144
	v_add_u32_e32 v226, s66, v143
	v_add_u32_e32 v227, s66, v144
	v_add_u32_e32 v228, s67, v143
	v_add_u32_e32 v229, s67, v144
	v_add_u32_e32 v230, s70, v143
	v_add_u32_e32 v231, s70, v144
	v_add_u32_e32 v232, s68, v143
	v_add_u32_e32 v233, s68, v144
	v_add_u32_e32 v234, s71, v143
	v_add_u32_e32 v235, s71, v144
	v_add_u32_e32 v236, s69, v143
	v_add_u32_e32 v237, s69, v144
.LBB0_1371:
	ds_read_b128 v[148:151], v222
	ds_read_b128 v[152:155], v223
	s_add_u32 s58, s18, s56
	ds_read_b128 v[158:161], v224
	ds_read_b128 v[162:165], v225
	s_addc_u32 s59, s19, s57
	ds_read_b128 v[170:173], v226
	ds_read_b128 v[174:177], v227
	s_add_u32 s58, s58, 0x100
	ds_read_b128 v[178:181], v228
	ds_read_b128 v[182:185], v229
	s_addc_u32 s59, s59, 0
	s_add_u32 s78, s53, s56
	s_addc_u32 s79, s72, s57
	s_cmpk_eq_i32 s56, 0x1f00
	s_cselect_b32 s79, s49, s79
	s_cselect_b32 s78, s76, s78
	s_cselect_b32 s59, s51, s59
	s_cselect_b32 s58, s73, s58
	v_lshl_add_u64 v[166:167], v[140:141], 0, s[56:57]
	v_lshl_add_u64 v[218:219], v[166:167], 0, s[24:25]
	s_add_i32 m0, s35, 0x8000
	ds_read_b128 v[186:189], v145
	ds_read_b128 v[190:193], v145 offset:2048
	ds_read_b128 v[194:197], v146
	ds_read_b128 v[198:201], v146 offset:2048
	ds_read_b128 v[202:205], v145 offset:4096
	ds_read_b128 v[206:209], v145 offset:6144
	ds_read_b128 v[210:213], v146 offset:4096
	ds_read_b128 v[214:217], v146 offset:6144
	global_load_lds_dwordx4 v[218:219], off
	v_lshl_add_u64 v[218:219], v[166:167], 0, s[44:45]
	s_add_i32 m0, s35, 0xa000
	s_nop 0
	global_load_lds_dwordx4 v[218:219], off
	v_lshl_add_u64 v[218:219], v[166:167], 0, s[28:29]
	s_add_i32 m0, s35, 0xc000
	v_lshl_add_u64 v[166:167], v[166:167], 0, s[46:47]
	global_load_lds_dwordx4 v[218:219], off
	s_add_i32 m0, s35, 0xe000
	s_nop 0
	global_load_lds_dwordx4 v[166:167], off
	s_waitcnt vmcnt(8)
	s_waitcnt lgkmcnt(0)
	s_barrier
	v_mfma_f32_16x16x32_bf16 v[128:131], v[148:151], v[186:189], v[128:131]
	v_mfma_f32_16x16x32_bf16 v[128:131], v[152:155], v[194:197], v[128:131]
	v_mfma_f32_16x16x32_bf16 v[112:115], v[152:155], v[198:201], v[112:115]
	v_mfma_f32_16x16x32_bf16 v[112:115], v[148:151], v[190:193], v[112:115]
	v_mfma_f32_16x16x32_bf16 v[96:99], v[148:151], v[202:205], v[96:99]
	v_mfma_f32_16x16x32_bf16 v[96:99], v[152:155], v[210:213], v[96:99]
	v_mfma_f32_16x16x32_bf16 v[80:83], v[152:155], v[214:217], v[80:83]
	v_mfma_f32_16x16x32_bf16 v[80:83], v[148:151], v[206:209], v[80:83]
	v_mfma_f32_16x16x32_bf16 v[76:79], v[158:161], v[206:209], v[76:79]
	v_mfma_f32_16x16x32_bf16 v[76:79], v[162:165], v[214:217], v[76:79]
	v_mfma_f32_16x16x32_bf16 v[92:95], v[162:165], v[210:213], v[92:95]
	v_mfma_f32_16x16x32_bf16 v[92:95], v[158:161], v[202:205], v[92:95]
	v_mfma_f32_16x16x32_bf16 v[108:111], v[158:161], v[190:193], v[108:111]
	v_mfma_f32_16x16x32_bf16 v[108:111], v[162:165], v[198:201], v[108:111]
	v_mfma_f32_16x16x32_bf16 v[124:127], v[162:165], v[194:197], v[124:127]
	v_mfma_f32_16x16x32_bf16 v[124:127], v[158:161], v[186:189], v[124:127]
	v_mfma_f32_16x16x32_bf16 v[120:123], v[170:173], v[186:189], v[120:123]
	v_mfma_f32_16x16x32_bf16 v[120:123], v[174:177], v[194:197], v[120:123]
	v_mfma_f32_16x16x32_bf16 v[104:107], v[174:177], v[198:201], v[104:107]
	v_mfma_f32_16x16x32_bf16 v[104:107], v[170:173], v[190:193], v[104:107]
	v_mfma_f32_16x16x32_bf16 v[88:91], v[170:173], v[202:205], v[88:91]
	v_mfma_f32_16x16x32_bf16 v[88:91], v[174:177], v[210:213], v[88:91]
	v_mfma_f32_16x16x32_bf16 v[72:75], v[174:177], v[214:217], v[72:75]
	v_mfma_f32_16x16x32_bf16 v[72:75], v[170:173], v[206:209], v[72:75]
	v_mfma_f32_16x16x32_bf16 v[68:71], v[178:181], v[206:209], v[68:71]
	v_mfma_f32_16x16x32_bf16 v[68:71], v[182:185], v[214:217], v[68:71]
	v_mfma_f32_16x16x32_bf16 v[84:87], v[182:185], v[210:213], v[84:87]
	v_mfma_f32_16x16x32_bf16 v[84:87], v[178:181], v[202:205], v[84:87]
	v_mfma_f32_16x16x32_bf16 v[100:103], v[178:181], v[190:193], v[100:103]
	v_mfma_f32_16x16x32_bf16 v[100:103], v[182:185], v[198:201], v[100:103]
	v_mfma_f32_16x16x32_bf16 v[116:119], v[182:185], v[194:197], v[116:119]
	v_mfma_f32_16x16x32_bf16 v[116:119], v[178:181], v[186:189], v[116:119]
	s_barrier
	v_lshl_add_u64 v[166:167], s[78:79], 0, v[132:133]
	s_add_i32 s78, s64, s34
	s_mov_b32 m0, s78
	ds_read_b128 v[186:189], v145 offset:16384
	ds_read_b128 v[190:193], v145 offset:18432
	ds_read_b128 v[194:197], v146 offset:16384
	ds_read_b128 v[198:201], v146 offset:18432
	ds_read_b128 v[202:205], v145 offset:20480
	ds_read_b128 v[206:209], v145 offset:22528
	ds_read_b128 v[210:213], v146 offset:20480
	ds_read_b128 v[214:217], v146 offset:22528
	global_load_lds_dwordx4 v[166:167], off
	v_lshl_add_u64 v[218:219], v[166:167], 0, s[10:11]
	s_add_i32 m0, s78, 0x2000
	s_add_i32 s78, s66, s34
	global_load_lds_dwordx4 v[218:219], off
	v_lshl_add_u64 v[218:219], v[166:167], 0, s[14:15]
	s_mov_b32 m0, s78
	s_nop 0
	global_load_lds_dwordx4 v[218:219], off
	v_lshl_add_u64 v[218:219], v[166:167], 0, s[16:17]
	s_add_i32 m0, s78, 0x2000
	s_nop 0
	global_load_lds_dwordx4 v[218:219], off
	s_waitcnt vmcnt(4)
	s_waitcnt lgkmcnt(0)
	s_barrier
	v_mfma_f32_16x16x32_bf16 v[64:67], v[148:151], v[186:189], v[64:67]
	v_mfma_f32_16x16x32_bf16 v[64:67], v[152:155], v[194:197], v[64:67]
	v_mfma_f32_16x16x32_bf16 v[48:51], v[152:155], v[198:201], v[48:51]
	v_mfma_f32_16x16x32_bf16 v[48:51], v[148:151], v[190:193], v[48:51]
	v_mfma_f32_16x16x32_bf16 v[32:35], v[148:151], v[202:205], v[32:35]
	v_mfma_f32_16x16x32_bf16 v[32:35], v[152:155], v[210:213], v[32:35]
	v_mfma_f32_16x16x32_bf16 v[16:19], v[152:155], v[214:217], v[16:19]
	v_mfma_f32_16x16x32_bf16 v[16:19], v[148:151], v[206:209], v[16:19]
	v_mfma_f32_16x16x32_bf16 v[12:15], v[158:161], v[206:209], v[12:15]
	v_mfma_f32_16x16x32_bf16 v[12:15], v[162:165], v[214:217], v[12:15]
	v_mfma_f32_16x16x32_bf16 v[28:31], v[162:165], v[210:213], v[28:31]
	v_mfma_f32_16x16x32_bf16 v[28:31], v[158:161], v[202:205], v[28:31]
	v_mfma_f32_16x16x32_bf16 v[44:47], v[158:161], v[190:193], v[44:47]
	v_mfma_f32_16x16x32_bf16 v[44:47], v[162:165], v[198:201], v[44:47]
	v_mfma_f32_16x16x32_bf16 v[60:63], v[162:165], v[194:197], v[60:63]
	v_mfma_f32_16x16x32_bf16 v[60:63], v[158:161], v[186:189], v[60:63]
	v_mfma_f32_16x16x32_bf16 v[56:59], v[170:173], v[186:189], v[56:59]
	v_mfma_f32_16x16x32_bf16 v[56:59], v[174:177], v[194:197], v[56:59]
	v_mfma_f32_16x16x32_bf16 v[40:43], v[174:177], v[198:201], v[40:43]
	v_mfma_f32_16x16x32_bf16 v[40:43], v[170:173], v[190:193], v[40:43]
	v_mfma_f32_16x16x32_bf16 v[24:27], v[170:173], v[202:205], v[24:27]
	v_mfma_f32_16x16x32_bf16 v[24:27], v[174:177], v[210:213], v[24:27]
	v_mfma_f32_16x16x32_bf16 v[8:11], v[174:177], v[214:217], v[8:11]
	v_mfma_f32_16x16x32_bf16 v[8:11], v[170:173], v[206:209], v[8:11]
	v_mfma_f32_16x16x32_bf16 v[4:7], v[178:181], v[206:209], v[4:7]
	v_mfma_f32_16x16x32_bf16 v[4:7], v[182:185], v[214:217], v[4:7]
	v_mfma_f32_16x16x32_bf16 v[20:23], v[182:185], v[210:213], v[20:23]
	v_mfma_f32_16x16x32_bf16 v[20:23], v[178:181], v[202:205], v[20:23]
	v_mfma_f32_16x16x32_bf16 v[36:39], v[178:181], v[190:193], v[36:39]
	v_mfma_f32_16x16x32_bf16 v[36:39], v[182:185], v[198:201], v[36:39]
	v_mfma_f32_16x16x32_bf16 v[52:55], v[182:185], v[194:197], v[52:55]
	v_mfma_f32_16x16x32_bf16 v[52:55], v[178:181], v[186:189], v[52:55]
	s_barrier
	ds_read_b128 v[148:151], v230
	ds_read_b128 v[152:155], v231
	ds_read_b128 v[158:161], v232
	ds_read_b128 v[162:165], v233
	ds_read_b128 v[170:173], v234
	ds_read_b128 v[174:177], v235
	ds_read_b128 v[178:181], v236
	ds_read_b128 v[182:185], v237
	s_mov_b32 m0, s35
	v_lshl_add_u64 v[218:219], s[58:59], 0, v[0:1]
	ds_read_b128 v[186:189], v145 offset:32768
	ds_read_b128 v[190:193], v145 offset:34816
	ds_read_b128 v[194:197], v146 offset:32768
	ds_read_b128 v[198:201], v146 offset:34816
	ds_read_b128 v[202:205], v145 offset:36864
	ds_read_b128 v[206:209], v145 offset:38912
	ds_read_b128 v[210:213], v146 offset:36864
	ds_read_b128 v[214:217], v146 offset:38912
	global_load_lds_dwordx4 v[218:219], off
	v_lshl_add_u64 v[220:221], v[218:219], 0, s[20:21]
	s_mov_b32 m0, s39
	s_nop 0
	global_load_lds_dwordx4 v[220:221], off
	v_lshl_add_u64 v[220:221], v[218:219], 0, s[10:11]
	s_mov_b32 m0, s60
	v_lshl_add_u64 v[218:219], v[218:219], 0, s[22:23]
	global_load_lds_dwordx4 v[220:221], off
	s_mov_b32 m0, s61
	s_nop 0
	global_load_lds_dwordx4 v[218:219], off
	s_waitcnt vmcnt(8)
	s_waitcnt lgkmcnt(0)
	s_barrier
	v_mfma_f32_16x16x32_bf16 v[128:131], v[148:151], v[186:189], v[128:131]
	v_mfma_f32_16x16x32_bf16 v[128:131], v[152:155], v[194:197], v[128:131]
	v_mfma_f32_16x16x32_bf16 v[112:115], v[152:155], v[198:201], v[112:115]
	v_mfma_f32_16x16x32_bf16 v[112:115], v[148:151], v[190:193], v[112:115]
	v_mfma_f32_16x16x32_bf16 v[96:99], v[148:151], v[202:205], v[96:99]
	v_mfma_f32_16x16x32_bf16 v[96:99], v[152:155], v[210:213], v[96:99]
	v_mfma_f32_16x16x32_bf16 v[80:83], v[152:155], v[214:217], v[80:83]
	v_mfma_f32_16x16x32_bf16 v[80:83], v[148:151], v[206:209], v[80:83]
	v_mfma_f32_16x16x32_bf16 v[76:79], v[158:161], v[206:209], v[76:79]
	v_mfma_f32_16x16x32_bf16 v[76:79], v[162:165], v[214:217], v[76:79]
	v_mfma_f32_16x16x32_bf16 v[92:95], v[162:165], v[210:213], v[92:95]
	v_mfma_f32_16x16x32_bf16 v[92:95], v[158:161], v[202:205], v[92:95]
	v_mfma_f32_16x16x32_bf16 v[108:111], v[158:161], v[190:193], v[108:111]
	v_mfma_f32_16x16x32_bf16 v[108:111], v[162:165], v[198:201], v[108:111]
	v_mfma_f32_16x16x32_bf16 v[124:127], v[162:165], v[194:197], v[124:127]
	v_mfma_f32_16x16x32_bf16 v[124:127], v[158:161], v[186:189], v[124:127]
	v_mfma_f32_16x16x32_bf16 v[120:123], v[170:173], v[186:189], v[120:123]
	v_mfma_f32_16x16x32_bf16 v[120:123], v[174:177], v[194:197], v[120:123]
	v_mfma_f32_16x16x32_bf16 v[104:107], v[174:177], v[198:201], v[104:107]
	v_mfma_f32_16x16x32_bf16 v[104:107], v[170:173], v[190:193], v[104:107]
	v_mfma_f32_16x16x32_bf16 v[88:91], v[170:173], v[202:205], v[88:91]
	v_mfma_f32_16x16x32_bf16 v[88:91], v[174:177], v[210:213], v[88:91]
	v_mfma_f32_16x16x32_bf16 v[72:75], v[174:177], v[214:217], v[72:75]
	v_mfma_f32_16x16x32_bf16 v[72:75], v[170:173], v[206:209], v[72:75]
	v_mfma_f32_16x16x32_bf16 v[68:71], v[178:181], v[206:209], v[68:71]
	v_mfma_f32_16x16x32_bf16 v[68:71], v[182:185], v[214:217], v[68:71]
	v_mfma_f32_16x16x32_bf16 v[84:87], v[182:185], v[210:213], v[84:87]
	v_mfma_f32_16x16x32_bf16 v[84:87], v[178:181], v[202:205], v[84:87]
	v_mfma_f32_16x16x32_bf16 v[100:103], v[178:181], v[190:193], v[100:103]
	v_mfma_f32_16x16x32_bf16 v[100:103], v[182:185], v[198:201], v[100:103]
	v_mfma_f32_16x16x32_bf16 v[116:119], v[182:185], v[194:197], v[116:119]
	v_mfma_f32_16x16x32_bf16 v[116:119], v[178:181], v[186:189], v[116:119]
	s_barrier
	s_add_i32 s58, s70, s34
	v_lshl_add_u64 v[218:219], v[166:167], 0, s[24:25]
	s_mov_b32 m0, s58
	ds_read_b128 v[186:189], v145 offset:49152
	ds_read_b128 v[190:193], v145 offset:51200
	ds_read_b128 v[194:197], v146 offset:49152
	ds_read_b128 v[198:201], v146 offset:51200
	ds_read_b128 v[202:205], v145 offset:53248
	ds_read_b128 v[206:209], v145 offset:55296
	ds_read_b128 v[210:213], v146 offset:53248
	ds_read_b128 v[214:217], v146 offset:55296
	global_load_lds_dwordx4 v[218:219], off
	v_lshl_add_u64 v[218:219], v[166:167], 0, s[28:29]
	s_add_i32 m0, s58, 0x2000
	s_add_i32 s58, s71, s34
	global_load_lds_dwordx4 v[218:219], off
	v_lshl_add_u64 v[218:219], v[166:167], 0, s[36:37]
	s_mov_b32 m0, s58
	v_lshl_add_u64 v[166:167], v[166:167], 0, s[40:41]
	global_load_lds_dwordx4 v[218:219], off
	s_add_i32 m0, s58, 0x2000
	s_nop 0
	global_load_lds_dwordx4 v[166:167], off
	s_waitcnt vmcnt(4)
	s_waitcnt lgkmcnt(0)
	s_barrier
	v_mfma_f32_16x16x32_bf16 v[64:67], v[148:151], v[186:189], v[64:67]
	v_mfma_f32_16x16x32_bf16 v[64:67], v[152:155], v[194:197], v[64:67]
	v_mfma_f32_16x16x32_bf16 v[48:51], v[152:155], v[198:201], v[48:51]
	v_mfma_f32_16x16x32_bf16 v[48:51], v[148:151], v[190:193], v[48:51]
	v_mfma_f32_16x16x32_bf16 v[32:35], v[148:151], v[202:205], v[32:35]
	v_mfma_f32_16x16x32_bf16 v[32:35], v[152:155], v[210:213], v[32:35]
	v_mfma_f32_16x16x32_bf16 v[16:19], v[152:155], v[214:217], v[16:19]
	v_mfma_f32_16x16x32_bf16 v[16:19], v[148:151], v[206:209], v[16:19]
	v_mfma_f32_16x16x32_bf16 v[12:15], v[158:161], v[206:209], v[12:15]
	v_mfma_f32_16x16x32_bf16 v[12:15], v[162:165], v[214:217], v[12:15]
	v_mfma_f32_16x16x32_bf16 v[28:31], v[162:165], v[210:213], v[28:31]
	v_mfma_f32_16x16x32_bf16 v[28:31], v[158:161], v[202:205], v[28:31]
	v_mfma_f32_16x16x32_bf16 v[44:47], v[158:161], v[190:193], v[44:47]
	v_mfma_f32_16x16x32_bf16 v[44:47], v[162:165], v[198:201], v[44:47]
	v_mfma_f32_16x16x32_bf16 v[60:63], v[162:165], v[194:197], v[60:63]
	v_mfma_f32_16x16x32_bf16 v[60:63], v[158:161], v[186:189], v[60:63]
	v_mfma_f32_16x16x32_bf16 v[56:59], v[170:173], v[186:189], v[56:59]
	v_mfma_f32_16x16x32_bf16 v[56:59], v[174:177], v[194:197], v[56:59]
	v_mfma_f32_16x16x32_bf16 v[40:43], v[174:177], v[198:201], v[40:43]
	v_mfma_f32_16x16x32_bf16 v[40:43], v[170:173], v[190:193], v[40:43]
	v_mfma_f32_16x16x32_bf16 v[24:27], v[170:173], v[202:205], v[24:27]
	v_mfma_f32_16x16x32_bf16 v[24:27], v[174:177], v[210:213], v[24:27]
	v_mfma_f32_16x16x32_bf16 v[8:11], v[174:177], v[214:217], v[8:11]
	v_mfma_f32_16x16x32_bf16 v[8:11], v[170:173], v[206:209], v[8:11]
	v_mfma_f32_16x16x32_bf16 v[4:7], v[178:181], v[206:209], v[4:7]
	v_mfma_f32_16x16x32_bf16 v[4:7], v[182:185], v[214:217], v[4:7]
	v_mfma_f32_16x16x32_bf16 v[20:23], v[182:185], v[210:213], v[20:23]
	v_mfma_f32_16x16x32_bf16 v[20:23], v[178:181], v[202:205], v[20:23]
	v_mfma_f32_16x16x32_bf16 v[36:39], v[178:181], v[190:193], v[36:39]
	v_mfma_f32_16x16x32_bf16 v[36:39], v[182:185], v[198:201], v[36:39]
	v_mfma_f32_16x16x32_bf16 v[52:55], v[182:185], v[194:197], v[52:55]
	v_mfma_f32_16x16x32_bf16 v[52:55], v[178:181], v[186:189], v[52:55]
	s_barrier
	s_add_i32 s77, s77, 2
	s_add_u32 s56, s56, 0x100
	s_addc_u32 s57, s57, 0
	s_cmp_gt_u32 s77, 61
	s_cbranch_scc0 .LBB0_1371
	s_add_u32 s56, s53, 0xffffff00
	s_addc_u32 s57, s72, -1
	s_andn2_b64 vcc, exec, s[6:7]
	s_cbranch_vccnz .LBB0_1362
	v_mov_b32_e32 v4, 0
	s_mov_b32 s0, s48
	s_mov_b32 s8, s50
	s_mov_b64 s[18:19], s[54:55]
	s_mov_b32 s63, s52
	v_mov_b32_e32 v5, v4
	v_mov_b32_e32 v6, v4
	v_mov_b32_e32 v7, v4
	v_mov_b32_e32 v8, v4
	v_mov_b32_e32 v9, v4
	v_mov_b32_e32 v10, v4
	v_mov_b32_e32 v11, v4
	v_mov_b32_e32 v20, v4
	v_mov_b32_e32 v21, v4
	v_mov_b32_e32 v22, v4
	v_mov_b32_e32 v23, v4
	v_mov_b32_e32 v24, v4
	v_mov_b32_e32 v25, v4
	v_mov_b32_e32 v26, v4
	v_mov_b32_e32 v27, v4
	v_mov_b32_e32 v36, v4
	v_mov_b32_e32 v37, v4
	v_mov_b32_e32 v38, v4
	v_mov_b32_e32 v39, v4
	v_mov_b32_e32 v40, v4
	v_mov_b32_e32 v41, v4
	v_mov_b32_e32 v42, v4
	v_mov_b32_e32 v43, v4
	v_mov_b32_e32 v52, v4
	v_mov_b32_e32 v53, v4
	v_mov_b32_e32 v54, v4
	v_mov_b32_e32 v55, v4
	v_mov_b32_e32 v56, v4
	v_mov_b32_e32 v57, v4
	v_mov_b32_e32 v58, v4
	v_mov_b32_e32 v59, v4
	v_mov_b32_e32 v12, v4
	v_mov_b32_e32 v13, v4
	v_mov_b32_e32 v14, v4
	v_mov_b32_e32 v15, v4
	v_mov_b32_e32 v16, v4
	v_mov_b32_e32 v17, v4
	v_mov_b32_e32 v18, v4
	v_mov_b32_e32 v19, v4
	v_mov_b32_e32 v28, v4
	v_mov_b32_e32 v29, v4
	v_mov_b32_e32 v30, v4
	v_mov_b32_e32 v31, v4
	v_mov_b32_e32 v32, v4
	v_mov_b32_e32 v33, v4
	v_mov_b32_e32 v34, v4
	v_mov_b32_e32 v35, v4
	v_mov_b32_e32 v44, v4
	v_mov_b32_e32 v45, v4
	v_mov_b32_e32 v46, v4
	v_mov_b32_e32 v47, v4
	v_mov_b32_e32 v48, v4
	v_mov_b32_e32 v49, v4
	v_mov_b32_e32 v50, v4
	v_mov_b32_e32 v51, v4
	v_mov_b32_e32 v60, v4
	v_mov_b32_e32 v61, v4
	v_mov_b32_e32 v62, v4
	v_mov_b32_e32 v63, v4
	v_mov_b32_e32 v64, v4
	v_mov_b32_e32 v65, v4
	v_mov_b32_e32 v66, v4
	v_mov_b32_e32 v67, v4
	v_mov_b32_e32 v68, v4
	v_mov_b32_e32 v69, v4
	v_mov_b32_e32 v70, v4
	v_mov_b32_e32 v71, v4
	v_mov_b32_e32 v72, v4
	v_mov_b32_e32 v73, v4
	v_mov_b32_e32 v74, v4
	v_mov_b32_e32 v75, v4
	v_mov_b32_e32 v84, v4
	v_mov_b32_e32 v85, v4
	v_mov_b32_e32 v86, v4
	v_mov_b32_e32 v87, v4
	v_mov_b32_e32 v88, v4
	v_mov_b32_e32 v89, v4
	v_mov_b32_e32 v90, v4
	v_mov_b32_e32 v91, v4
	v_mov_b32_e32 v100, v4
	v_mov_b32_e32 v101, v4
	v_mov_b32_e32 v102, v4
	v_mov_b32_e32 v103, v4
	v_mov_b32_e32 v104, v4
	v_mov_b32_e32 v105, v4
	v_mov_b32_e32 v106, v4
	v_mov_b32_e32 v107, v4
	v_mov_b32_e32 v116, v4
	v_mov_b32_e32 v117, v4
	v_mov_b32_e32 v118, v4
	v_mov_b32_e32 v119, v4
	v_mov_b32_e32 v120, v4
	v_mov_b32_e32 v121, v4
	v_mov_b32_e32 v122, v4
	v_mov_b32_e32 v123, v4
	v_mov_b32_e32 v76, v4
	v_mov_b32_e32 v77, v4
	v_mov_b32_e32 v78, v4
	v_mov_b32_e32 v79, v4
	v_mov_b32_e32 v80, v4
	v_mov_b32_e32 v81, v4
	v_mov_b32_e32 v82, v4
	v_mov_b32_e32 v83, v4
	v_mov_b32_e32 v92, v4
	v_mov_b32_e32 v93, v4
	v_mov_b32_e32 v94, v4
	v_mov_b32_e32 v95, v4
	v_mov_b32_e32 v96, v4
	v_mov_b32_e32 v97, v4
	v_mov_b32_e32 v98, v4
	v_mov_b32_e32 v99, v4
	v_mov_b32_e32 v108, v4
	v_mov_b32_e32 v109, v4
	v_mov_b32_e32 v110, v4
	v_mov_b32_e32 v111, v4
	v_mov_b32_e32 v112, v4
	v_mov_b32_e32 v113, v4
	v_mov_b32_e32 v114, v4
	v_mov_b32_e32 v115, v4
	v_mov_b32_e32 v124, v4
	v_mov_b32_e32 v125, v4
	v_mov_b32_e32 v126, v4
	v_mov_b32_e32 v127, v4
	v_mov_b32_e32 v128, v4
	v_mov_b32_e32 v129, v4
	v_mov_b32_e32 v130, v4
	v_mov_b32_e32 v131, v4
	s_andn2_b64 vcc, exec, s[4:5]
	s_cbranch_vccnz .LBB0_1363
